# v19 pool-epilogue batching with unreachable nop padding so the following GEMM loops keep v13 code placement
# speedup vs baseline: 1.0007x; 1.0007x over previous
; __device__ __forceinline__ float bflo(unsigned w) { return __uint_as_float(w << 16); }
; __device__ __forceinline__ float bfhi(unsigned w) { return __uint_as_float(w & 0xffff0000u); }
;     __device__ __forceinline__ void operator()(f32x4 (&acc)[2][2][4][2], const Unit& u, int wr, int wc, int fr, int fq) const {
;     ...
;         for (int ai = 0; ai < 2; ++ai)
; #pragma unroll
;             for (int m = 0; m < 4; ++m) { const size_t row = (size_t)(row0 + ai * HALF + m * 16);
; #pragma unroll
;                 for (int bj = 0; bj < 2; ++bj) { const int col = col0 + bj * HALF;
;                     const u32x4 gt = *(const u32x4*)(HM + row * HMW + C_AGATE + col);
;                     const f32x4 v0 = acc[ai][bj][m][0], v1 = acc[ai][bj][m][1];
;                     u32x4 w; w.x = pk2(v0[0] * bflo(gt.x), v0[1] * bfhi(gt.x)); w.y = pk2(v0[2] * bflo(gt.y), v0[3] * bfhi(gt.y));
;                     w.z = pk2(v1[0] * bflo(gt.z), v1[1] * bfhi(gt.z)); w.w = pk2(v1[2] * bflo(gt.w), v1[3] * bfhi(gt.w));
.LBB0_623:
	s_mov_b64 s[86:87], -1
	s_waitcnt vmcnt(15)
	v_lshlrev_b32_e32 v226, 16, v148
	v_and_b32_e32 v227, 0xffff0000, v148
	v_lshlrev_b32_e32 v228, 16, v149
	v_and_b32_e32 v229, 0xffff0000, v149
	v_lshlrev_b32_e32 v230, 16, v150
	v_and_b32_e32 v231, 0xffff0000, v150
	v_lshlrev_b32_e32 v232, 16, v151
	v_and_b32_e32 v233, 0xffff0000, v151
	v_mul_f32_e32 v126, v126, v226
	v_mul_f32_e32 v127, v127, v227
	v_mul_f32_e32 v128, v128, v228
	v_mul_f32_e32 v129, v129, v229
	v_mul_f32_e32 v122, v122, v230
	v_mul_f32_e32 v123, v123, v231
	v_mul_f32_e32 v124, v124, v232
	v_mul_f32_e32 v125, v125, v233
	s_waitcnt vmcnt(14)
	v_lshlrev_b32_e32 v226, 16, v158
	v_and_b32_e32 v227, 0xffff0000, v158
	v_lshlrev_b32_e32 v228, 16, v159
	v_and_b32_e32 v229, 0xffff0000, v159
	v_lshlrev_b32_e32 v230, 16, v160
	v_and_b32_e32 v231, 0xffff0000, v160
	v_lshlrev_b32_e32 v232, 16, v161
	v_and_b32_e32 v233, 0xffff0000, v161
	v_mul_f32_e32 v118, v118, v226
	v_mul_f32_e32 v119, v119, v227
	v_mul_f32_e32 v120, v120, v228
	v_mul_f32_e32 v121, v121, v229
	v_mul_f32_e32 v114, v114, v230
	v_mul_f32_e32 v115, v115, v231
	v_mul_f32_e32 v116, v116, v232
	v_mul_f32_e32 v117, v117, v233
	s_waitcnt vmcnt(13)
	v_lshlrev_b32_e32 v226, 16, v162
	v_and_b32_e32 v227, 0xffff0000, v162
	v_lshlrev_b32_e32 v228, 16, v163
	v_and_b32_e32 v229, 0xffff0000, v163
	v_lshlrev_b32_e32 v230, 16, v164
	v_and_b32_e32 v231, 0xffff0000, v164
	v_lshlrev_b32_e32 v232, 16, v165
	v_and_b32_e32 v233, 0xffff0000, v165
	v_mul_f32_e32 v110, v110, v226
	v_mul_f32_e32 v111, v111, v227
	v_mul_f32_e32 v112, v112, v228
	v_mul_f32_e32 v113, v113, v229
	v_mul_f32_e32 v106, v106, v230
	v_mul_f32_e32 v107, v107, v231
	v_mul_f32_e32 v108, v108, v232
	v_mul_f32_e32 v109, v109, v233
	s_waitcnt vmcnt(12)
	v_lshlrev_b32_e32 v226, 16, v174
	v_and_b32_e32 v227, 0xffff0000, v174
	v_lshlrev_b32_e32 v228, 16, v175
	v_and_b32_e32 v229, 0xffff0000, v175
	v_lshlrev_b32_e32 v230, 16, v176
	v_and_b32_e32 v231, 0xffff0000, v176
	v_lshlrev_b32_e32 v232, 16, v177
	v_and_b32_e32 v233, 0xffff0000, v177
	v_mul_f32_e32 v102, v102, v226
	v_mul_f32_e32 v103, v103, v227
	v_mul_f32_e32 v104, v104, v228
	v_mul_f32_e32 v105, v105, v229
	v_mul_f32_e32 v98, v98, v230
	v_mul_f32_e32 v99, v99, v231
	v_mul_f32_e32 v100, v100, v232
	v_mul_f32_e32 v101, v101, v233
	s_waitcnt vmcnt(11)
	v_lshlrev_b32_e32 v226, 16, v178
	v_and_b32_e32 v227, 0xffff0000, v178
	v_lshlrev_b32_e32 v228, 16, v179
	v_and_b32_e32 v229, 0xffff0000, v179
	v_lshlrev_b32_e32 v230, 16, v180
	v_and_b32_e32 v231, 0xffff0000, v180
	v_lshlrev_b32_e32 v232, 16, v181
	v_and_b32_e32 v233, 0xffff0000, v181
	v_mul_f32_e32 v94, v94, v226
	v_mul_f32_e32 v95, v95, v227
	v_mul_f32_e32 v96, v96, v228
	v_mul_f32_e32 v97, v97, v229
	v_mul_f32_e32 v90, v90, v230
	v_mul_f32_e32 v91, v91, v231
	v_mul_f32_e32 v92, v92, v232
	v_mul_f32_e32 v93, v93, v233
	s_waitcnt vmcnt(10)
	v_lshlrev_b32_e32 v226, 16, v182
	v_and_b32_e32 v227, 0xffff0000, v182
	v_lshlrev_b32_e32 v228, 16, v183
	v_and_b32_e32 v229, 0xffff0000, v183
	v_lshlrev_b32_e32 v230, 16, v184
	v_and_b32_e32 v231, 0xffff0000, v184
	v_lshlrev_b32_e32 v232, 16, v185
	v_and_b32_e32 v233, 0xffff0000, v185
	v_mul_f32_e32 v86, v86, v226
	v_mul_f32_e32 v87, v87, v227
	v_mul_f32_e32 v88, v88, v228
	v_mul_f32_e32 v89, v89, v229
	v_mul_f32_e32 v82, v82, v230
	v_mul_f32_e32 v83, v83, v231
	v_mul_f32_e32 v84, v84, v232
	v_mul_f32_e32 v85, v85, v233
	s_waitcnt vmcnt(9)
	v_lshlrev_b32_e32 v226, 16, v186
	v_and_b32_e32 v227, 0xffff0000, v186
	v_lshlrev_b32_e32 v228, 16, v187
	v_and_b32_e32 v229, 0xffff0000, v187
	v_lshlrev_b32_e32 v230, 16, v188
	v_and_b32_e32 v231, 0xffff0000, v188
	v_lshlrev_b32_e32 v232, 16, v189
	v_and_b32_e32 v233, 0xffff0000, v189
	v_mul_f32_e32 v78, v78, v226
	v_mul_f32_e32 v79, v79, v227
	v_mul_f32_e32 v80, v80, v228
	v_mul_f32_e32 v81, v81, v229
	v_mul_f32_e32 v74, v74, v230
	v_mul_f32_e32 v75, v75, v231
	v_mul_f32_e32 v76, v76, v232
	v_mul_f32_e32 v77, v77, v233
	s_waitcnt vmcnt(8)
	v_lshlrev_b32_e32 v226, 16, v190
	v_and_b32_e32 v227, 0xffff0000, v190
	v_lshlrev_b32_e32 v228, 16, v191
	v_and_b32_e32 v229, 0xffff0000, v191
	v_lshlrev_b32_e32 v230, 16, v192
	v_and_b32_e32 v231, 0xffff0000, v192
	v_lshlrev_b32_e32 v232, 16, v193
	v_and_b32_e32 v233, 0xffff0000, v193
	v_mul_f32_e32 v70, v70, v226
	v_mul_f32_e32 v71, v71, v227
	v_mul_f32_e32 v72, v72, v228
	v_mul_f32_e32 v73, v73, v229
	v_mul_f32_e32 v66, v66, v230
	v_mul_f32_e32 v67, v67, v231
	v_mul_f32_e32 v68, v68, v232
	v_mul_f32_e32 v69, v69, v233
	s_waitcnt vmcnt(7)
	v_lshlrev_b32_e32 v226, 16, v194
	v_and_b32_e32 v227, 0xffff0000, v194
	v_lshlrev_b32_e32 v228, 16, v195
	v_and_b32_e32 v229, 0xffff0000, v195
	v_lshlrev_b32_e32 v230, 16, v196
	v_and_b32_e32 v231, 0xffff0000, v196
	v_lshlrev_b32_e32 v232, 16, v197
	v_and_b32_e32 v233, 0xffff0000, v197
	v_mul_f32_e32 v62, v62, v226
	v_mul_f32_e32 v63, v63, v227
	v_mul_f32_e32 v64, v64, v228
	v_mul_f32_e32 v65, v65, v229
	v_mul_f32_e32 v58, v58, v230
	v_mul_f32_e32 v59, v59, v231
	v_mul_f32_e32 v60, v60, v232
	v_mul_f32_e32 v61, v61, v233
	s_waitcnt vmcnt(6)
	v_lshlrev_b32_e32 v226, 16, v198
	v_and_b32_e32 v227, 0xffff0000, v198
	v_lshlrev_b32_e32 v228, 16, v199
	v_and_b32_e32 v229, 0xffff0000, v199
	v_lshlrev_b32_e32 v230, 16, v200
	v_and_b32_e32 v231, 0xffff0000, v200
	v_lshlrev_b32_e32 v232, 16, v201
	v_and_b32_e32 v233, 0xffff0000, v201
	v_mul_f32_e32 v54, v54, v226
	v_mul_f32_e32 v55, v55, v227
	v_mul_f32_e32 v56, v56, v228
	v_mul_f32_e32 v57, v57, v229
	v_mul_f32_e32 v50, v50, v230
	v_mul_f32_e32 v51, v51, v231
	v_mul_f32_e32 v52, v52, v232
	v_mul_f32_e32 v53, v53, v233
	s_waitcnt vmcnt(5)
; __device__ __forceinline__ float bflo(unsigned w) { return __uint_as_float(w << 16); }
; __device__ __forceinline__ float bfhi(unsigned w) { return __uint_as_float(w & 0xffff0000u); }
;     __device__ __forceinline__ void operator()(f32x4 (&acc)[2][2][4][2], const Unit& u, int wr, int wc, int fr, int fq) const {
;     ...
;                     const u32x4 gt = *(const u32x4*)(HM + row * HMW + C_AGATE + col);
;                     const f32x4 v0 = acc[ai][bj][m][0], v1 = acc[ai][bj][m][1];
;                     u32x4 w; w.x = pk2(v0[0] * bflo(gt.x), v0[1] * bfhi(gt.x)); w.y = pk2(v0[2] * bflo(gt.y), v0[3] * bfhi(gt.y));
;                     w.z = pk2(v1[0] * bflo(gt.z), v1[1] * bfhi(gt.z)); w.w = pk2(v1[2] * bflo(gt.w), v1[3] * bfhi(gt.w));
;                     *(u32x4*)(YA + row * 1024 + col) = w; } }
	v_lshlrev_b32_e32 v226, 16, v202
	v_and_b32_e32 v227, 0xffff0000, v202
	v_lshlrev_b32_e32 v228, 16, v203
	v_and_b32_e32 v229, 0xffff0000, v203
	v_lshlrev_b32_e32 v230, 16, v204
	v_and_b32_e32 v231, 0xffff0000, v204
	v_lshlrev_b32_e32 v232, 16, v205
	v_and_b32_e32 v233, 0xffff0000, v205
	v_mul_f32_e32 v46, v46, v226
	v_mul_f32_e32 v47, v47, v227
	v_mul_f32_e32 v48, v48, v228
	v_mul_f32_e32 v49, v49, v229
	v_mul_f32_e32 v42, v42, v230
	v_mul_f32_e32 v43, v43, v231
	v_mul_f32_e32 v44, v44, v232
	v_mul_f32_e32 v45, v45, v233
	s_waitcnt vmcnt(4)
	v_lshlrev_b32_e32 v226, 16, v206
	v_and_b32_e32 v227, 0xffff0000, v206
	v_lshlrev_b32_e32 v228, 16, v207
	v_and_b32_e32 v229, 0xffff0000, v207
	v_lshlrev_b32_e32 v230, 16, v208
	v_and_b32_e32 v231, 0xffff0000, v208
	v_lshlrev_b32_e32 v232, 16, v209
	v_and_b32_e32 v233, 0xffff0000, v209
	v_mul_f32_e32 v38, v38, v226
	v_mul_f32_e32 v39, v39, v227
	v_mul_f32_e32 v40, v40, v228
	v_mul_f32_e32 v41, v41, v229
	v_mul_f32_e32 v34, v34, v230
	v_mul_f32_e32 v35, v35, v231
	v_mul_f32_e32 v36, v36, v232
	v_mul_f32_e32 v37, v37, v233
	s_waitcnt vmcnt(3)
	v_lshlrev_b32_e32 v226, 16, v210
	v_and_b32_e32 v227, 0xffff0000, v210
	v_lshlrev_b32_e32 v228, 16, v211
	v_and_b32_e32 v229, 0xffff0000, v211
	v_lshlrev_b32_e32 v230, 16, v212
	v_and_b32_e32 v231, 0xffff0000, v212
	v_lshlrev_b32_e32 v232, 16, v213
	v_and_b32_e32 v233, 0xffff0000, v213
	v_mul_f32_e32 v30, v30, v226
	v_mul_f32_e32 v31, v31, v227
	v_mul_f32_e32 v32, v32, v228
	v_mul_f32_e32 v33, v33, v229
	v_mul_f32_e32 v26, v26, v230
	v_mul_f32_e32 v27, v27, v231
	v_mul_f32_e32 v28, v28, v232
	v_mul_f32_e32 v29, v29, v233
	s_waitcnt vmcnt(2)
	v_lshlrev_b32_e32 v226, 16, v214
	v_and_b32_e32 v227, 0xffff0000, v214
	v_lshlrev_b32_e32 v228, 16, v215
	v_and_b32_e32 v229, 0xffff0000, v215
	v_lshlrev_b32_e32 v230, 16, v216
	v_and_b32_e32 v231, 0xffff0000, v216
	v_lshlrev_b32_e32 v232, 16, v217
	v_and_b32_e32 v233, 0xffff0000, v217
	v_mul_f32_e32 v22, v22, v226
	v_mul_f32_e32 v23, v23, v227
	v_mul_f32_e32 v24, v24, v228
	v_mul_f32_e32 v25, v25, v229
	v_mul_f32_e32 v18, v18, v230
	v_mul_f32_e32 v19, v19, v231
	v_mul_f32_e32 v20, v20, v232
	v_mul_f32_e32 v21, v21, v233
	s_waitcnt vmcnt(1)
	v_lshlrev_b32_e32 v226, 16, v218
	v_and_b32_e32 v227, 0xffff0000, v218
	v_lshlrev_b32_e32 v228, 16, v219
	v_and_b32_e32 v229, 0xffff0000, v219
	v_lshlrev_b32_e32 v230, 16, v220
	v_and_b32_e32 v231, 0xffff0000, v220
	v_lshlrev_b32_e32 v232, 16, v221
	v_and_b32_e32 v233, 0xffff0000, v221
	v_mul_f32_e32 v14, v14, v226
	v_mul_f32_e32 v15, v15, v227
	v_mul_f32_e32 v16, v16, v228
	v_mul_f32_e32 v17, v17, v229
	v_mul_f32_e32 v10, v10, v230
	v_mul_f32_e32 v11, v11, v231
	v_mul_f32_e32 v12, v12, v232
	v_mul_f32_e32 v13, v13, v233
	s_waitcnt vmcnt(0)
	v_lshlrev_b32_e32 v226, 16, v222
	v_and_b32_e32 v227, 0xffff0000, v222
	v_lshlrev_b32_e32 v228, 16, v223
	v_and_b32_e32 v229, 0xffff0000, v223
	v_lshlrev_b32_e32 v230, 16, v224
	v_and_b32_e32 v231, 0xffff0000, v224
	v_lshlrev_b32_e32 v232, 16, v225
	v_and_b32_e32 v233, 0xffff0000, v225
	v_mul_f32_e32 v6, v6, v226
	v_mul_f32_e32 v7, v7, v227
	v_mul_f32_e32 v8, v8, v228
	v_mul_f32_e32 v9, v9, v229
	v_mul_f32_e32 v2, v2, v230
	v_mul_f32_e32 v3, v3, v231
	v_mul_f32_e32 v4, v4, v232
	v_mul_f32_e32 v5, v5, v233
	v_lshl_add_u32 v234, v152, 11, v153
	v_cvt_pk_bf16_f32 v148, v126, v127
	v_cvt_pk_bf16_f32 v149, v128, v129
	v_cvt_pk_bf16_f32 v150, v122, v123
	v_cvt_pk_bf16_f32 v151, v124, v125
	global_store_dwordx4 v234, v[148:151], s[38:39]
	v_cvt_pk_bf16_f32 v158, v118, v119
	v_cvt_pk_bf16_f32 v159, v120, v121
	v_cvt_pk_bf16_f32 v160, v114, v115
	v_cvt_pk_bf16_f32 v161, v116, v117
	global_store_dwordx4 v234, v[158:161], s[38:39] offset:256
	v_add_u32_e32 v235, 0x8000, v234
	v_cvt_pk_bf16_f32 v162, v110, v111
	v_cvt_pk_bf16_f32 v163, v112, v113
	v_cvt_pk_bf16_f32 v164, v106, v107
	v_cvt_pk_bf16_f32 v165, v108, v109
	global_store_dwordx4 v235, v[162:165], s[38:39]
	v_cvt_pk_bf16_f32 v174, v102, v103
	v_cvt_pk_bf16_f32 v175, v104, v105
	v_cvt_pk_bf16_f32 v176, v98, v99
	v_cvt_pk_bf16_f32 v177, v100, v101
	global_store_dwordx4 v235, v[174:177], s[38:39] offset:256
	v_add_u32_e32 v235, 0x10000, v234
	v_cvt_pk_bf16_f32 v178, v94, v95
	v_cvt_pk_bf16_f32 v179, v96, v97
	v_cvt_pk_bf16_f32 v180, v90, v91
	v_cvt_pk_bf16_f32 v181, v92, v93
	global_store_dwordx4 v235, v[178:181], s[38:39]
	v_cvt_pk_bf16_f32 v182, v86, v87
	v_cvt_pk_bf16_f32 v183, v88, v89
	v_cvt_pk_bf16_f32 v184, v82, v83
	v_cvt_pk_bf16_f32 v185, v84, v85
	global_store_dwordx4 v235, v[182:185], s[38:39] offset:256
	v_add_u32_e32 v235, 0x18000, v234
	v_cvt_pk_bf16_f32 v186, v78, v79
	v_cvt_pk_bf16_f32 v187, v80, v81
	v_cvt_pk_bf16_f32 v188, v74, v75
	v_cvt_pk_bf16_f32 v189, v76, v77
	global_store_dwordx4 v235, v[186:189], s[38:39]
	v_cvt_pk_bf16_f32 v190, v70, v71
	v_cvt_pk_bf16_f32 v191, v72, v73
	v_cvt_pk_bf16_f32 v192, v66, v67
	v_cvt_pk_bf16_f32 v193, v68, v69
	global_store_dwordx4 v235, v[190:193], s[38:39] offset:256
	v_add_u32_e32 v235, 0x40000, v234
	v_cvt_pk_bf16_f32 v194, v62, v63
	v_cvt_pk_bf16_f32 v195, v64, v65
	v_cvt_pk_bf16_f32 v196, v58, v59
	v_cvt_pk_bf16_f32 v197, v60, v61
	global_store_dwordx4 v235, v[194:197], s[38:39]
	v_cvt_pk_bf16_f32 v198, v54, v55
	v_cvt_pk_bf16_f32 v199, v56, v57
	v_cvt_pk_bf16_f32 v200, v50, v51
	v_cvt_pk_bf16_f32 v201, v52, v53
	global_store_dwordx4 v235, v[198:201], s[38:39] offset:256
	v_add_u32_e32 v235, 0x48000, v234
	v_cvt_pk_bf16_f32 v202, v46, v47
	v_cvt_pk_bf16_f32 v203, v48, v49
	v_cvt_pk_bf16_f32 v204, v42, v43
	v_cvt_pk_bf16_f32 v205, v44, v45
	global_store_dwordx4 v235, v[202:205], s[38:39]
	v_cvt_pk_bf16_f32 v206, v38, v39
	v_cvt_pk_bf16_f32 v207, v40, v41
	v_cvt_pk_bf16_f32 v208, v34, v35
	v_cvt_pk_bf16_f32 v209, v36, v37
	global_store_dwordx4 v235, v[206:209], s[38:39] offset:256
	v_add_u32_e32 v235, 0x50000, v234
	v_cvt_pk_bf16_f32 v210, v30, v31
	v_cvt_pk_bf16_f32 v211, v32, v33
	v_cvt_pk_bf16_f32 v212, v26, v27
	v_cvt_pk_bf16_f32 v213, v28, v29
	global_store_dwordx4 v235, v[210:213], s[38:39]
	v_cvt_pk_bf16_f32 v214, v22, v23
	v_cvt_pk_bf16_f32 v215, v24, v25
	v_cvt_pk_bf16_f32 v216, v18, v19
	v_cvt_pk_bf16_f32 v217, v20, v21
	global_store_dwordx4 v235, v[214:217], s[38:39] offset:256
	v_add_u32_e32 v235, 0x58000, v234
	v_cvt_pk_bf16_f32 v218, v14, v15
	v_cvt_pk_bf16_f32 v219, v16, v17
	v_cvt_pk_bf16_f32 v220, v10, v11
	v_cvt_pk_bf16_f32 v221, v12, v13
	global_store_dwordx4 v235, v[218:221], s[38:39]
	v_cvt_pk_bf16_f32 v222, v6, v7
	v_cvt_pk_bf16_f32 v223, v8, v9
	v_cvt_pk_bf16_f32 v224, v2, v3
	v_cvt_pk_bf16_f32 v225, v4, v5
	global_store_dwordx4 v235, v[222:225], s[38:39] offset:256
	s_and_b64 vcc, exec, s[40:41]
	s_cbranch_vccnz .LBB0_612
; #define PG8_BAR __builtin_amdgcn_s_barrier()
;     __device__ __forceinline__ bool zero_after(const Unit& u) const { return (u.pm >> 6) == 3; }
; template <bool ALIGN_EPI, bool SP2, class Epi, class Sched>
; __device__ __forceinline__ void gemm_phase(LAS unsigned char* lds, const Gemm g, const Sched& S, const Epi& E) {
;     ...
;         if (!has_next) break;
;         if (E.zero_after(cur))
; #pragma unroll
;         for (int a = 0; a < 2; ++a)
; #pragma unroll
;             for (int b = 0; b < 2; ++b)
; #pragma unroll
;                 for (int m = 0; m < 4; ++m)
; #pragma unroll
;                     for (int n = 0; n < 2; ++n) acc[a][b][m][n] = (f32x4){0.f, 0.f, 0.f, 0.f};
;         cur = nxt; cA = nA; cB = nB; ++ui;
;         if constexpr (ALIGN_EPI) { if (wr == 1) PG8_BAR; }
	s_andn2_b64 vcc, exec, s[34:35]
	s_cbranch_vccnz .LBB0_611
	s_barrier
	s_branch .LBB0_611
	s_nop 0
	s_nop 0
	s_nop 0
	s_nop 0
	s_nop 0
	s_nop 0
	s_nop 0
	s_nop 0
	s_nop 0
	s_nop 0
	s_nop 0
	s_nop 0
	s_nop 0
	s_nop 0
	s_nop 0
	s_nop 0
	s_nop 0
	s_nop 0
	s_nop 0
	s_nop 0
	s_nop 0
	s_nop 0
	s_nop 0
	s_nop 0
	s_nop 0
	s_nop 0
	s_nop 0
	s_nop 0
	s_nop 0
	s_nop 0
	s_nop 0
	s_nop 0
	s_nop 0
	s_nop 0
	s_nop 0
	s_nop 0
	s_nop 0
	s_nop 0
	s_nop 0
	s_nop 0
	s_nop 0
	s_nop 0
	s_nop 0
	s_nop 0
	s_nop 0
	s_nop 0
	s_nop 0
	s_nop 0
	s_nop 0
	s_nop 0
	s_nop 0
	s_nop 0
	s_nop 0
	s_nop 0
	s_nop 0
	s_nop 0
	s_nop 0
	s_nop 0
	s_nop 0
	s_nop 0
	s_nop 0
	s_nop 0
	s_nop 0
	s_nop 0
	s_nop 0
	s_nop 0
	s_nop 0
	s_nop 0
	s_nop 0
	s_nop 0
	s_nop 0
	s_nop 0
	s_nop 0
	s_nop 0
	s_nop 0
	s_nop 0
	s_nop 0
	s_nop 0
	s_nop 0
	s_nop 0
	s_nop 0
	s_nop 0
	s_nop 0
	s_nop 0
	s_nop 0
	s_nop 0
	s_nop 0
	s_nop 0
	s_nop 0
	s_nop 0
	s_nop 0
	s_nop 0
